# c13 + phase 9: the 256 sample tokens handed out by a work queue (WGs that finish their quads early take more)
# baseline (speedup 1.0000x reference)
.LBB0_1755:
	v_readlane_b32 s42, v254, 40
	v_readlane_b32 s44, v254, 42
	v_readlane_b32 s43, v254, 41
	v_readlane_b32 s45, v254, 43
	s_waitcnt vmcnt(0) lgkmcnt(0)
	s_cmp_lg_u32 s80, 1
	s_cbranch_scc1 .Lsq_a
	v_mbcnt_lo_u32_b32 v0, -1, 0
	v_mbcnt_hi_u32_b32 v0, -1, v0
	v_cmp_eq_u32_e32 vcc, 0, v0
	s_and_saveexec_b64 s[8:9], vcc
	v_mov_b32_e32 v0, 0
	v_mov_b32_e32 v1, 1
	global_atomic_add v1, v0, v1, s[78:79] offset:2048 sc0
	s_waitcnt vmcnt(0)
	v_mov_b32_e32 v0, 0x25200
	ds_write_b32 v0, v1
	s_waitcnt lgkmcnt(0)
	s_or_b64 exec, exec, s[8:9]
.Lsq_a:
	s_barrier
	v_mov_b32_e32 v0, 0x25200
	ds_read_b32 v0, v0
	s_waitcnt lgkmcnt(0)
	v_readfirstlane_b32 s16, v0
	s_nop 3
	s_add_i32 s16, s16, 0x8000
	s_cmp_gt_i32 s16, 0x80ff
	s_cbranch_scc1 .LBB0_1762
	s_add_u32 s0, s78, 0x1e447000
	s_addc_u32 s1, s79, 0
	s_add_u32 s17, s78, 0xa1d9000
	s_addc_u32 s18, s79, 0
	s_add_u32 s2, s78, 0x1dc37000
	s_addc_u32 s3, s79, 0
	s_add_u32 s19, s78, 0xc219000
	s_addc_u32 s20, s79, 0
	s_add_u32 s4, s78, 0x1e457000
	s_addc_u32 s5, s79, 0
	s_lshl_b32 s6, s80, 6
	s_add_u32 s21, s40, s6
	s_addc_u32 s22, s41, 0
	s_lshl_b32 s23, s80, 12
	s_add_i32 s23, s23, 0x10000
	s_add_u32 s24, s78, 0x18931000
	s_mov_b32 s6, 0x36800020
	s_addc_u32 s25, s79, 0
	v_mov_b32_e32 v9, 0
	s_mov_b32 s26, 0xf0f0f00
	s_mov_b32 s27, 0xc0c0500
	s_mov_b32 s28, 0x2000604
	v_mov_b32_e32 v11, 0x40f00000
	s_mov_b32 s7, 0.5
	s_mov_b32 s29, 0x3ea7ba05
	v_mov_b32_e32 v134, 0xbfba00e3
	s_brev_b32 s30, -2
	s_mov_b32 s31, 0x800000
	s_branch .LBB0_1758
.LBB0_1757:
	s_cmp_lg_u32 s80, 1
	s_cbranch_scc1 .Lsq_b
	v_mbcnt_lo_u32_b32 v0, -1, 0
	v_mbcnt_hi_u32_b32 v0, -1, v0
	v_cmp_eq_u32_e32 vcc, 0, v0
	s_and_saveexec_b64 s[8:9], vcc
	v_mov_b32_e32 v0, 0
	v_mov_b32_e32 v1, 1
	global_atomic_add v1, v0, v1, s[78:79] offset:2048 sc0
	s_waitcnt vmcnt(0)
	v_mov_b32_e32 v0, 0x25200
	ds_write_b32 v0, v1
	s_waitcnt lgkmcnt(0)
	s_or_b64 exec, exec, s[8:9]
.Lsq_b:
	s_barrier
	v_mov_b32_e32 v0, 0x25200
	ds_read_b32 v0, v0
	s_waitcnt lgkmcnt(0)
	v_readfirstlane_b32 s16, v0
	s_nop 3
	s_add_i32 s16, s16, 0x8000
	s_cmp_gt_i32 s16, 0x80ff
	s_cbranch_scc1 .LBB0_1762
